# v055 plus first K/V tile loads of the cmp2 pass issued above the psl zeroing loop and of the window pass issued above the block selection
# speedup vs baseline: 1.0035x; 1.0035x over previous
; DI void cmpwin_unit(const Params& P, lptr L, int u, int tid, int lane, int wid) {
;     ...
;         float l = rs.l; l += __shfl_xor(l, 32);
;         const float mfin = (l > 0.f) ? rs.mref + __builtin_amdgcn_logf(l) : 0.f;
;         for (int e = tid; e < 257 * PSL_P; e += 512) psl[e] = 0.f;
;         __syncthreads();
;         f32x16 o0, o1;
; #pragma unroll
;         for (int r = 0; r < 16; ++r) { o0[r] = 0.f; o1[r] = 0.f; }
;         ATT_LOOP_BEGIN(NTC, false, kb_ + (size_t)(jt * 64) * 64, vb_ + (size_t)jt * 64, (const float*)nullptr)
.LBB0_542:
	global_load_dwordx4 v[66:69], v[74:75], off
	global_load_dwordx4 v[70:73], v[76:77], off
	v_and_b32_e32 v3, 64, v209
	v_xor_b32_e32 v2, 32, v209
	v_add_u32_e32 v3, 64, v3
	v_cmp_lt_i32_e32 vcc, v2, v3
	s_mov_b64 s[0:1], 0
	v_mov_b32_e32 v3, v199
	v_cndmask_b32_e32 v2, v209, v2, vcc
	v_lshlrev_b32_e32 v149, 2, v2
	ds_bpermute_b32 v2, v149, v46
	v_mov_b32_e32 v4, v198
.LBB0_543:
	v_add_u32_e32 v3, 0x200, v3
	s_movk_i32 s2, 0x3f40
	v_cmp_lt_u32_e32 vcc, s2, v3
	ds_write_b32 v4, v1
	s_or_b64 s[0:1], vcc, s[0:1]
	v_add_u32_e32 v4, 0x800, v4
	s_andn2_b64 exec, exec, s[0:1]
	s_cbranch_execnz .LBB0_543
	s_or_b64 exec, exec, s[0:1]
	s_waitcnt lgkmcnt(0)
	s_barrier
	v_add_f32_e32 v3, v46, v2
	v_log_f32_e32 v2, v3
	v_cmp_lt_f32_e32 vcc, 0, v3
	s_mov_b32 s24, 0
	s_waitcnt vmcnt(1)
	ds_write_b128 v127, v[66:69]
	s_waitcnt vmcnt(0)
	ds_write_b128 v127, v[70:73] offset:18432
	v_add_f32_e32 v4, v51, v2
	v_mov_b32_e32 v2, 0
	v_cndmask_b32_e32 v87, 0, v4, vcc
	v_mov_b32_e32 v3, v2
	v_mov_b32_e32 v4, v2
	v_mov_b32_e32 v5, v2
	v_mov_b32_e32 v6, v2
	v_mov_b32_e32 v7, v2
	v_mov_b32_e32 v8, v2
	v_mov_b32_e32 v9, v2
	v_mov_b32_e32 v10, v2
	v_mov_b32_e32 v11, v2
	v_mov_b32_e32 v12, v2
	v_mov_b32_e32 v13, v2
	v_mov_b32_e32 v14, v2
	v_mov_b32_e32 v15, v2
	v_mov_b32_e32 v16, v2
	v_mov_b32_e32 v17, v2
	v_mov_b32_e32 v18, v2
	v_mov_b32_e32 v19, v2
	v_mov_b32_e32 v20, v2
	v_mov_b32_e32 v21, v2
	v_mov_b32_e32 v22, v2
	v_mov_b32_e32 v23, v2
	v_mov_b32_e32 v24, v2
	v_mov_b32_e32 v25, v2
	v_mov_b32_e32 v26, v2
	v_mov_b32_e32 v27, v2
	v_mov_b32_e32 v28, v2
	v_mov_b32_e32 v29, v2
	v_mov_b32_e32 v30, v2
	v_mov_b32_e32 v31, v2
	v_mov_b32_e32 v32, v2
	v_mov_b32_e32 v33, v2
	s_waitcnt lgkmcnt(0)
	s_barrier
	s_branch .LBB0_546

; #define LAS __attribute__((address_space(3)))
; DI void cmpwin_unit(const Params& P, lptr L, int u, int tid, int lane, int wid) {
;     ...
;         {
;             const LAS float* tp_ = (const LAS float*)(L + AL_TMP) + ((NTC - 1) & 1) * (8 * 17 * 32);
;             for (int e = tid; e < 2 * 17 * 32; e += 512) { const int q32 = e & 31, jl = (e >> 5) % 17, qh = e / (17 * 32);
;                 const float a = (tp_[((qh * 4 + 0) * 17 + jl) * 32 + q32] + tp_[((qh * 4 + 1) * 17 + jl) * 32 + q32]) + (tp_[((qh * 4 + 2) * 17 + jl) * 32 + q32] + tp_[((qh * 4 + 3) * 17 + jl) * 32 + q32]);
;                 psl[((NTC - 1) * 16 + jl) * PSL_P + qh * 32 + q32] += a; }
;             __syncthreads();
;         }
;         float* prow = PART + row * 512 + head * 64;
; #pragma unroll
;         for (int g4 = 0; g4 < 4; ++g4) {
;             *(f32x4*)(prow + 8 * g4 + 4 * hi) = (f32x4){o0[4 * g4] * gc, o0[4 * g4 + 1] * gc, o0[4 * g4 + 2] * gc, o0[4 * g4 + 3] * gc};
;             *(f32x4*)(prow + 32 + 8 * g4 + 4 * hi) = (f32x4){o1[4 * g4] * gc, o1[4 * g4 + 1] * gc, o1[4 * g4 + 2] * gc, o1[4 * g4 + 3] * gc};
;         }
;     ...
;         const int jw0 = max(0, qb - 8), NTW = qb - jw0 + 1;
;         const bf16_t* kb_ = PROJ + (size_t)(b * SEQ) * PROJ_LD + 1664 + g * 64; const size_t kpitch_ = PROJ_LD;
;         const bf16_t* vb_ = VT + (size_t)((b * 12 + 10 + g) * 64) * VTP; const size_t vpitch_ = VTP;
;         ATT_LOOP_BEGIN(NTW, false, kb_ + (size_t)((jw0 + jt) * 64) * PROJ_LD, vb_ + (size_t)(jw0 + jt) * 64, (const float*)nullptr)
.LBB0_559:
	v_subrev_u32_e32 v37, 17, v35
	v_cmp_gt_u32_e32 vcc, s11, v36
	s_nop 1
	v_cndmask_b32_e32 v37, v37, v35, vcc
	v_cmp_lt_u32_e32 vcc, s76, v36
	v_add_u32_e32 v35, 16, v35
	s_nop 0
	v_cndmask_b32_e32 v38, 0, v212, vcc
	v_add_u32_e32 v38, v37, v38
	v_lshl_add_u32 v39, v38, 7, v34
	ds_read_b32 v38, v39
	ds_read_b32 v40, v39 offset:2176
	ds_read_b32 v41, v39 offset:4352
	ds_read_b32 v39, v39 offset:6528
	v_add_u32_e32 v37, s2, v37
	v_mul_lo_u32 v37, v37, s6
	v_add_u32_e32 v37, 0, v37
	s_waitcnt lgkmcnt(0)
	v_pk_add_f32 v[38:39], v[40:41], v[38:39]
	s_nop 0
	v_add_f32_e32 v38, v38, v39
	v_cndmask_b32_e32 v39, 0, v213, vcc
	v_lshlrev_b32_e32 v40, 2, v122
	v_add3_u32 v37, v37, v39, v40
	ds_read_b32 v39, v37 offset:37888
	v_cmp_lt_u32_e32 vcc, s77, v36
	s_or_b64 s[0:1], vcc, s[0:1]
	s_waitcnt lgkmcnt(0)
	v_add_f32_e32 v38, v39, v38
	ds_write_b32 v37, v38 offset:37888
	v_add_u32_e32 v37, 0x200, v36
	v_mov_b32_e32 v36, v37
	s_andn2_b64 exec, exec, s[0:1]
	s_cbranch_execnz .LBB0_559
	s_or_b64 exec, exec, s[0:1]
	v_add_f32_e32 v34, 1.0, v84
	v_div_scale_f32 v35, s[0:1], v34, v34, 1.0
	v_rcp_f32_e32 v36, v35
	v_div_scale_f32 v37, vcc, 1.0, v34, 1.0
	s_lshl_b32 s60, s51, 2
	v_fma_f32 v38, -v35, v36, 1.0
	v_fmac_f32_e32 v36, v38, v36
	v_mul_f32_e32 v38, v37, v36
	v_fma_f32 v39, -v35, v38, v37
	v_readlane_b32 s0, v250, 0
	v_fmac_f32_e32 v38, v39, v36
	v_readlane_b32 s1, v250, 1
	s_add_u32 s0, s0, s60
	v_fma_f32 v35, -v35, v38, v37
	s_addc_u32 s1, s1, 0
	v_div_fmas_f32 v35, v35, v36, v38
	v_lshlrev_b64 v[36:37], 11, v[0:1]
	s_cmpk_eq_i32 s61, 0xfe
	v_lshl_add_u64 v[36:37], s[0:1], 0, v[36:37]
	s_cselect_b32 s0, -2, -3
	s_cmpk_lg_i32 s61, 0xff
	s_cselect_b32 s33, s0, -1
	s_sub_i32 s1, 0x100, s61
	s_sub_i32 s2, 0xfd, s61
	s_min_u32 s1, s1, 16
	s_max_i32 s0, s2, 0
	s_add_i32 s33, s33, s1
	s_sub_i32 s3, 0xfe, s61
	v_div_fixup_f32 v34, v35, v34, 1.0
	v_lshlrev_b32_e32 v154, 2, v134
	v_mov_b32_e32 v155, v1
	s_cmp_lt_i32 s33, s0
	v_readlane_b32 s0, v250, 23
	v_lshl_add_u64 v[158:159], v[36:37], 0, v[154:155]
	v_pk_mul_f32 v[2:3], v[34:35], v[2:3] op_sel_hi:[0,1]
	v_pk_mul_f32 v[4:5], v[34:35], v[4:5] op_sel_hi:[0,1]
	v_cmp_ge_i32_e32 vcc, s2, v192
	v_readlane_b32 s1, v250, 24
	s_waitcnt lgkmcnt(0)
	s_barrier
	global_store_dwordx4 v[158:159], v[2:5], off
	s_cselect_b64 s[28:29], -1, 0
	s_and_b64 s[70:71], s[0:1], vcc
	v_pk_mul_f32 v[2:3], v[34:35], v[18:19] op_sel_hi:[0,1]
	v_pk_mul_f32 v[4:5], v[34:35], v[20:21] op_sel_hi:[0,1]
	v_cmp_eq_u32_e32 vcc, s41, v192
	global_store_dwordx4 v[158:159], v[2:5], off offset:128
	s_or_b64 s[0:1], s[12:13], vcc
	v_cmp_eq_u32_e32 vcc, s3, v192
	v_pk_mul_f32 v[2:3], v[34:35], v[6:7] op_sel_hi:[0,1]
	v_pk_mul_f32 v[4:5], v[34:35], v[8:9] op_sel_hi:[0,1]
	global_store_dwordx4 v[158:159], v[2:5], off offset:32
	s_or_b64 s[78:79], s[0:1], vcc
	v_cmp_eq_u32_e32 vcc, s41, v175
	v_pk_mul_f32 v[2:3], v[34:35], v[22:23] op_sel_hi:[0,1]
	v_pk_mul_f32 v[4:5], v[34:35], v[24:25] op_sel_hi:[0,1]
	v_cmp_eq_u32_e64 s[0:1], s3, v175
	global_store_dwordx4 v[158:159], v[2:5], off offset:160
	s_or_b64 s[30:31], vcc, s[0:1]
	v_cmp_eq_u32_e32 vcc, s41, v176
	v_pk_mul_f32 v[2:3], v[34:35], v[10:11] op_sel_hi:[0,1]
	v_pk_mul_f32 v[4:5], v[34:35], v[12:13] op_sel_hi:[0,1]
	v_cmp_eq_u32_e64 s[0:1], s3, v176
	global_store_dwordx4 v[158:159], v[2:5], off offset:64
	s_or_b64 s[64:65], vcc, s[0:1]
	v_cmp_eq_u32_e32 vcc, s41, v178
	v_pk_mul_f32 v[2:3], v[34:35], v[26:27] op_sel_hi:[0,1]
	v_pk_mul_f32 v[4:5], v[34:35], v[28:29] op_sel_hi:[0,1]
	v_cmp_eq_u32_e64 s[0:1], s3, v178
	global_store_dwordx4 v[158:159], v[2:5], off offset:192
	v_cmp_ge_i32_e64 s[22:23], s2, v175
	v_cmp_ge_i32_e64 s[24:25], s2, v176
	v_pk_mul_f32 v[2:3], v[34:35], v[14:15] op_sel_hi:[0,1]
	v_pk_mul_f32 v[4:5], v[34:35], v[16:17] op_sel_hi:[0,1]
	v_cmp_ge_i32_e64 s[26:27], s2, v178
	s_or_b64 s[74:75], vcc, s[0:1]
	global_store_dwordx4 v[158:159], v[2:5], off offset:96
	s_mov_b32 s82, 0
	s_mov_b32 s39, s41
	v_pk_mul_f32 v[2:3], v[34:35], v[30:31] op_sel_hi:[0,1]
	v_pk_mul_f32 v[4:5], v[34:35], v[32:33] op_sel_hi:[0,1]
	s_or_b64 s[68:69], s[78:79], s[70:71]
	s_or_b64 s[2:3], s[30:31], s[22:23]
	s_or_b64 s[42:43], s[64:65], s[24:25]
	s_or_b64 s[58:59], s[74:75], s[26:27]
	global_store_dwordx4 v[158:159], v[2:5], off offset:224
	s_sub_i32 s0, 0xf7, s61
	s_max_i32 s22, s0, 0
	s_mul_i32 s0, s63, 0x4200000
	v_readlane_b32 s24, v251, 58
	v_readlane_b32 s25, v251, 59
	s_add_u32 s0, s24, s0
	s_addc_u32 s1, s25, 0
	s_lshl_b32 s24, s48, 7
	s_add_u32 s0, s0, s24
	s_addc_u32 s1, s1, 0
	s_mul_i32 s24, s63, 12
	s_or_b32 s24, s24, s48
	s_mul_i32 s24, s24, 0x202000
	s_add_i32 s24, s24, 0x1414000
	v_readlane_b32 s25, v251, 60
	s_add_u32 s24, s25, s24
	v_readlane_b32 s25, v251, 61
	s_addc_u32 s25, s25, 0
	s_mov_b32 s23, 0
	s_lshl_b32 s43, s22, 6
	s_lshl_b64 s[26:27], s[22:23], 7
	s_add_u32 s24, s24, s26
	s_addc_u32 s25, s25, s27
	s_mul_i32 s26, s22, 0x42000
	s_mul_hi_u32 s27, s43, 0x1080
	s_add_u32 s0, s0, s26
	s_addc_u32 s1, s1, s27
	v_lshlrev_b32_e32 v26, 1, v132
	v_mov_b32_e32 v27, v1
	v_lshl_add_u64 v[28:29], s[24:25], 0, v[26:27]
	v_lshlrev_b32_e32 v26, 1, v128
; #define LAS __attribute__((address_space(3)))
; DI void cmpwin_unit(const Params& P, lptr L, int u, int tid, int lane, int wid) {
;     ...
;         for (int qq = 0; qq < 8; ++qq) {
;             const int q = wid * 8 + qq; const int tq = qb * 64 + q;
;             unsigned key[4]; bool cand[4], selb[4];
; #pragma unroll
;             for (int ii = 0; ii < 4; ++ii) { const int j = lane + 64 * ii; key[ii] = __float_as_uint(psl[j * PSL_P + q]);
;                 cand[ii] = (j >= 1) && (j <= cur - 2); selb[ii] = (j == 0) || (j == cur) || (j == cur - 1); }
;             if (K >= ncand) {
; #pragma unroll
;                 for (int ii = 0; ii < 4; ++ii) selb[ii] = selb[ii] || cand[ii];
;             } else {
;                 unsigned tau = 0u;
;     ...
;                     const unsigned trial = tau | (1u << bit);
;                     int cnt = 0;
; #pragma unroll
;                     for (int ii = 0; ii < 4; ++ii) cnt += __popcll(__ballot(cand[ii] && key[ii] >= trial));
;                     if (cnt == K) { tau = trial - 1u; break; }
;                     if (cnt > K) tau = trial;
;                 }
;                 int cgt = 0;
; #pragma unroll
;                 for (int ii = 0; ii < 4; ++ii) cgt += __popcll(__ballot(cand[ii] && key[ii] > tau));
;                 int need = K - cgt;
; #pragma unroll
;                 for (int ii = 0; ii < 4; ++ii) {
;                     const bool eq = cand[ii] && key[ii] == tau;
;                     const unsigned long long bal = __ballot(eq);
;                     const int rank = __popcll(bal & lt_mask);
;                     selb[ii] = selb[ii] || (cand[ii] && key[ii] > tau) || (eq && rank < need);
;                     need = max(0, need - (int)__popcll(bal));
;                 }
;             }
;             LAS unsigned* mrow = (LAS unsigned*)(L + AL_SM) + q * 8; (void)tq;
; #pragma unroll
;             for (int ii = 0; ii < 4; ++ii) { const unsigned long long bal = __ballot(selb[ii]); if (lane == 0) { mrow[2 * ii] = (unsigned)bal; mrow[2 * ii + 1] = (unsigned)(bal >> 32); } }
;     ...
;         const bf16_t* kb_ = PROJ + (size_t)(b * SEQ) * PROJ_LD + 1664 + g * 64; const size_t kpitch_ = PROJ_LD;
;         const bf16_t* vb_ = VT + (size_t)((b * 12 + 10 + g) * 64) * VTP; const size_t vpitch_ = VTP;
;         ATT_LOOP_BEGIN(NTW, false, kb_ + (size_t)((jw0 + jt) * 64) * PROJ_LD, vb_ + (size_t)(jw0 + jt) * 64, (const float*)nullptr)
	v_lshl_add_u64 v[30:31], s[0:1], 0, v[26:27]
	v_lshlrev_b32_e32 v26, 1, v130
	v_lshl_add_u64 v[30:31], v[30:31], 0, v[26:27]
	v_lshl_add_u64 v[28:29], v[28:29], 0, v[26:27]
	global_load_dwordx4 v[114:117], v[30:31], off offset:3328
	global_load_dwordx4 v[118:121], v[28:29], off
	v_and_b32_e32 v12, 7, v192
	v_lshrrev_b32_e32 v13, 3, v192
	v_add_u32_e32 v13, s93, v13
	v_lshlrev_b32_e32 v14, 5, v12
	v_mov_b32_e32 v0, 0x410
	v_mul_u32_u24_e32 v15, 0x2080, v12
	v_lshl_add_u32 v15, v13, 2, v15
	v_add_u32_e32 v26, 0, v12
	v_and_b32_e32 v26, 7, v26
	v_mad_u32_u24 v26, v26, v0, v15
	v_add_u32_e32 v27, 1, v12
	v_and_b32_e32 v27, 7, v27
	v_mad_u32_u24 v27, v27, v0, v15
	v_add_u32_e32 v28, 2, v12
	v_and_b32_e32 v28, 7, v28
	v_mad_u32_u24 v28, v28, v0, v15
	v_add_u32_e32 v29, 3, v12
	v_and_b32_e32 v29, 7, v29
	v_mad_u32_u24 v29, v29, v0, v15
	v_add_u32_e32 v30, 4, v12
	v_and_b32_e32 v30, 7, v30
	v_mad_u32_u24 v30, v30, v0, v15
	v_add_u32_e32 v31, 5, v12
	v_and_b32_e32 v31, 7, v31
	v_mad_u32_u24 v31, v31, v0, v15
	v_add_u32_e32 v32, 6, v12
	v_and_b32_e32 v32, 7, v32
	v_mad_u32_u24 v32, v32, v0, v15
	v_add_u32_e32 v33, 7, v12
	v_and_b32_e32 v33, 7, v33
	v_mad_u32_u24 v33, v33, v0, v15
	ds_read_b32 v228, v26 offset:37888
	ds_read_b32 v229, v26 offset:38148
	ds_read_b32 v230, v26 offset:38408
	ds_read_b32 v231, v26 offset:38668
	ds_read_b32 v232, v27 offset:37888
	ds_read_b32 v233, v27 offset:38148
	ds_read_b32 v234, v27 offset:38408
	ds_read_b32 v235, v27 offset:38668
	ds_read_b32 v236, v28 offset:37888
	ds_read_b32 v237, v28 offset:38148
	ds_read_b32 v238, v28 offset:38408
	ds_read_b32 v239, v28 offset:38668
	ds_read_b32 v240, v29 offset:37888
	ds_read_b32 v241, v29 offset:38148
	ds_read_b32 v242, v29 offset:38408
	ds_read_b32 v243, v29 offset:38668
	ds_read_b32 v244, v30 offset:37888
	ds_read_b32 v245, v30 offset:38148
	ds_read_b32 v246, v30 offset:38408
	ds_read_b32 v247, v30 offset:38668
	ds_read_b32 v248, v31 offset:37888
	ds_read_b32 v17, v31 offset:38148
	ds_read_b32 v252, v31 offset:38408
	ds_read_b32 v253, v31 offset:38668
	ds_read_b32 v254, v32 offset:37888
	ds_read_b32 v255, v32 offset:38148
	ds_read_b32 v6, v32 offset:38408
	ds_read_b32 v7, v32 offset:38668
	ds_read_b32 v8, v33 offset:37888
	ds_read_b32 v9, v33 offset:38148
	ds_read_b32 v10, v33 offset:38408
	ds_read_b32 v11, v33 offset:38668
	v_lshlrev_b32_e32 v2, 2, v12
	v_sub_u32_e32 v3, 32, v2
	v_and_b32_e32 v3, 31, v3
	s_add_i32 s100, s39, -1
	s_lshl_b32 s101, s93, 5
	s_add_i32 s101, s101, 0x19904
	v_mov_b32_e32 v18, 1
	v_mov_b32_e32 v19, 0
	v_sub_u32_e32 v16, s100, v14
	v_max_i32_e32 v16, 0, v16
	v_min_i32_e32 v16, 32, v16
	v_lshlrev_b64 v[20:21], v16, v[18:19]
	v_add_u32_e32 v22, -1, v20
	v_cmp_eq_u32_e32 vcc, 0, v12
	s_nop 1
	v_cndmask_b32_e64 v23, 0, 1, vcc
	v_xor_b32_e32 v24, -1, v23
	v_and_b32_e32 v22, v22, v24
	v_sub_u32_e32 v25, s39, v14
	v_cmp_gt_u32_e32 vcc, 32, v25
	v_lshlrev_b32_e64 v24, v25, 1
	s_nop 0
	v_cndmask_b32_e32 v24, 0, v24, vcc
	v_or_b32_e32 v23, v23, v24
	v_sub_u32_e32 v25, s100, v14
	v_cmp_gt_u32_e32 vcc, 32, v25
	v_lshlrev_b32_e64 v24, v25, 1
	s_nop 0
	v_cndmask_b32_e32 v24, 0, v24, vcc
	v_or_b32_e32 v23, v23, v24
	v_or_b32_e32 v32, v23, v22
	s_and_b64 vcc, exec, s[28:29]
	s_cbranch_vccz .Lsel_store
	s_waitcnt lgkmcnt(0)
	v_alignbit_b32 v4, v22, v22, v2
	v_bfe_i32 v24, v4, 0, 1
	v_and_b32_e32 v228, v228, v24
	v_bfe_i32 v25, v4, 1, 1
	v_and_b32_e32 v229, v229, v25
	v_bfe_i32 v24, v4, 2, 1
	v_and_b32_e32 v230, v230, v24
	v_bfe_i32 v25, v4, 3, 1
	v_and_b32_e32 v231, v231, v25
	v_bfe_i32 v24, v4, 4, 1
	v_and_b32_e32 v232, v232, v24
	v_bfe_i32 v25, v4, 5, 1
	v_and_b32_e32 v233, v233, v25
	v_bfe_i32 v24, v4, 6, 1
	v_and_b32_e32 v234, v234, v24
	v_bfe_i32 v25, v4, 7, 1
	v_and_b32_e32 v235, v235, v25
	v_bfe_i32 v24, v4, 8, 1
	v_and_b32_e32 v236, v236, v24
	v_bfe_i32 v25, v4, 9, 1
	v_and_b32_e32 v237, v237, v25
	v_bfe_i32 v24, v4, 10, 1
	v_and_b32_e32 v238, v238, v24
	v_bfe_i32 v25, v4, 11, 1
	v_and_b32_e32 v239, v239, v25
	v_bfe_i32 v24, v4, 12, 1
	v_and_b32_e32 v240, v240, v24
	v_bfe_i32 v25, v4, 13, 1
	v_and_b32_e32 v241, v241, v25
	v_bfe_i32 v24, v4, 14, 1
	v_and_b32_e32 v242, v242, v24
	v_bfe_i32 v25, v4, 15, 1
	v_and_b32_e32 v243, v243, v25
	v_bfe_i32 v24, v4, 16, 1
	v_and_b32_e32 v244, v244, v24
	v_bfe_i32 v25, v4, 17, 1
	v_and_b32_e32 v245, v245, v25
	v_bfe_i32 v24, v4, 18, 1
	v_and_b32_e32 v246, v246, v24
	v_bfe_i32 v25, v4, 19, 1
	v_and_b32_e32 v247, v247, v25
	v_bfe_i32 v24, v4, 20, 1
	v_and_b32_e32 v248, v248, v24
	v_bfe_i32 v25, v4, 21, 1
	v_and_b32_e32 v17, v17, v25
	v_bfe_i32 v24, v4, 22, 1
	v_and_b32_e32 v252, v252, v24
	v_bfe_i32 v25, v4, 23, 1
	v_and_b32_e32 v253, v253, v25
	v_bfe_i32 v24, v4, 24, 1
	v_and_b32_e32 v254, v254, v24
	v_bfe_i32 v25, v4, 25, 1
	v_and_b32_e32 v255, v255, v25
	v_bfe_i32 v24, v4, 26, 1
	v_and_b32_e32 v6, v6, v24
	v_bfe_i32 v25, v4, 27, 1
	v_and_b32_e32 v7, v7, v25
	v_bfe_i32 v24, v4, 28, 1
	v_and_b32_e32 v8, v8, v24
	v_bfe_i32 v25, v4, 29, 1
	v_and_b32_e32 v9, v9, v25
	v_bfe_i32 v24, v4, 30, 1
	v_and_b32_e32 v10, v10, v24
	v_bfe_i32 v25, v4, 31, 1
	v_and_b32_e32 v11, v11, v25
	v_mov_b32_e32 v26, 0
	s_mov_b64 s[52:53], 0
	s_mov_b32 s98, 30

; DI void cmpwin_unit(const Params& P, lptr L, int u, int tid, int lane, int wid) {
;     ...
;     for (int rp_ = 0; rp_ < ((PROBE_SUB & 4) ? 2 : 1); ++rp_)
;     {
;         f32x16 o0, o1;
; #pragma unroll
;         for (int r = 0; r < 16; ++r) { o0[r] = 0.f; o1[r] = 0.f; }
;         RowState rs; rs.mref = 0.f; rs.l = 0.f; rs.seen = false;
;         const int jw0 = max(0, qb - 8), NTW = qb - jw0 + 1;
;         const bf16_t* kb_ = PROJ + (size_t)(b * SEQ) * PROJ_LD + 1664 + g * 64; const size_t kpitch_ = PROJ_LD;
;         const bf16_t* vb_ = VT + (size_t)((b * 12 + 10 + g) * 64) * VTP; const size_t vpitch_ = VTP;
;         ATT_LOOP_BEGIN(NTW, false, kb_ + (size_t)((jw0 + jt) * 64) * PROJ_LD, vb_ + (size_t)(jw0 + jt) * 64, (const float*)nullptr)
;             const int kv0 = (jw0 + jt) * 64;
;             TP tp; tp.cs = nullptr; tp.sl = sl; tp.fb = sl * (float)(kv0 + 8 * hi - t); tp.lim = t - kv0 - 8 * hi; tp.lim2 = tp.lim - 512; tp.sel = true;
.LBB0_578:
	s_sub_i32 s0, 0xf7, s61
	s_max_i32 s22, s0, 0
	s_sub_i32 s42, s39, s22
	s_mul_i32 s0, s63, 0x4200000
	v_readlane_b32 s2, v251, 58
	v_readlane_b32 s3, v251, 59
	s_add_u32 s0, s2, s0
	s_addc_u32 s1, s3, 0
	s_lshl_b32 s2, s48, 7
	s_add_u32 s0, s0, s2
	s_mul_i32 s33, s63, 12
	s_addc_u32 s1, s1, 0
	s_or_b32 s2, s33, s48
	s_mul_i32 s2, s2, 0x202000
	s_add_i32 s2, s2, 0x1414000
	v_readlane_b32 s3, v251, 60
	s_add_u32 s2, s3, s2
	v_readlane_b32 s3, v251, 61
	s_mov_b32 s23, s83
	s_addc_u32 s3, s3, 0
	s_lshl_b32 s43, s22, 6
	s_lshl_b64 s[24:25], s[22:23], 7
	s_add_u32 s24, s2, s24
	s_mul_i32 s26, s22, 0x42000
	s_addc_u32 s25, s3, s25
	v_lshlrev_b32_e32 v160, 1, v132
	v_mov_b32_e32 v161, v1
	s_mul_hi_u32 s27, s43, 0x1080
	v_lshl_add_u64 v[2:3], s[24:25], 0, v[160:161]
	s_add_u32 s24, s0, s26
	v_lshlrev_b32_e32 v162, 1, v128
	v_mov_b32_e32 v163, v1
	s_addc_u32 s25, s1, s27
	v_lshl_add_u64 v[4:5], s[24:25], 0, v[162:163]
	v_lshlrev_b32_e32 v0, 1, v130
	v_lshl_add_u64 v[4:5], v[4:5], 0, v[0:1]
	v_lshl_add_u64 v[2:3], v[2:3], 0, v[0:1]
	v_lshl_add_u64 v[2:3], s[0:1], 0, v[162:163]
	v_lshl_add_u64 v[156:157], v[2:3], 0, v[0:1]
	s_cmp_gt_i32 s42, -1
	s_waitcnt vmcnt(1)
	ds_write_b128 v127, v[114:117]
	s_waitcnt vmcnt(0)
	ds_write_b128 v127, v[118:121] offset:18432
	s_waitcnt lgkmcnt(0)
	s_barrier
	s_cbranch_scc0 .LBB0_597
	v_lshl_add_u64 v[2:3], s[2:3], 0, v[160:161]
	v_lshl_add_u64 v[164:165], v[2:3], 0, v[0:1]
	v_add_u32_e32 v2, s62, v200
	v_mov_b32_e32 v16, v1
	v_mov_b32_e32 v17, v1
	v_subrev_u32_e32 v155, s43, v2
	s_add_i32 s52, s61, s22
	v_mov_b32_e32 v2, v1
	v_mov_b32_e32 v3, v1
	v_mov_b32_e32 v4, v1
	v_mov_b32_e32 v5, v1
	v_mov_b32_e32 v6, v1
	v_mov_b32_e32 v7, v1
	v_mov_b32_e32 v8, v1
	v_mov_b32_e32 v9, v1
	v_mov_b32_e32 v10, v1
	v_mov_b32_e32 v11, v1
	v_mov_b32_e32 v12, v1
	v_mov_b32_e32 v13, v1
	v_mov_b32_e32 v14, v1
	v_mov_b32_e32 v15, v1
	v_mov_b64_e32 v[32:33], v[16:17]
	s_add_i32 s23, s81, 0xfffffe20
	v_mov_b32_e32 v166, v150
	v_mov_b32_e32 v167, v150
	v_mov_b32_e32 v168, v150
	v_mov_b32_e32 v169, v150
	v_subrev_u32_e32 v161, s62, v201
	s_addk_i32 s52, 0xff00
	s_mov_b32 s53, 0
	s_mov_b64 s[24:25], 0
	v_mov_b32_e32 v163, 0
	v_mov_b32_e32 v215, 0
	v_mov_b64_e32 v[30:31], v[14:15]
	v_mov_b64_e32 v[28:29], v[12:13]
	v_mov_b64_e32 v[26:27], v[10:11]
	v_mov_b64_e32 v[24:25], v[8:9]
	v_mov_b64_e32 v[22:23], v[6:7]
	v_mov_b64_e32 v[20:21], v[4:5]
	v_mov_b64_e32 v[18:19], v[2:3]
	s_cmp_lt_i32 s53, s42
	s_cselect_b64 s[26:27], -1, 0
	s_cmp_ge_i32 s53, s42
	s_cbranch_scc1 .LBB0_581
